# spatial unit prologue: w_spatial loads issued ahead of the V^T staging wait and barrier
# baseline (speedup 1.0000x reference)
.LBB0_136:
	s_or_b64 exec, exec, s[6:7]
	v_and_b32_e32 v44, 3, v2
	v_mul_u32_u24_e32 v0, 0x180000, v44
	v_readlane_b32 s6, v217, 37
	v_lshlrev_b32_e32 v0, 1, v0
	v_readlane_b32 s7, v217, 38
	v_bfe_i32 v5, v56, 27, 1
	v_lshrrev_b32_e32 v5, 22, v5
	v_lshl_add_u64 v[2:3], s[6:7], 0, v[0:1]
	v_lshlrev_b32_e32 v0, 1, v60
	v_lshl_add_u64 v[2:3], v[2:3], 0, v[0:1]
	v_lshlrev_b32_e32 v0, 4, v56
	v_add_u32_e32 v5, v0, v5
	v_and_b32_e32 v5, 0xfffffc00, v5
	v_ashrrev_i32_e32 v4, 31, v56
	v_sub_u32_e32 v5, v0, v5
	v_lshrrev_b32_e32 v4, 26, v4
	v_lshrrev_b32_e32 v6, 4, v5
	v_add_u32_e32 v4, v56, v4
	v_bitop3_b32 v6, v6, v5, 32 bitop3:0x6c
	v_ashrrev_i32_e32 v5, 31, v5
	v_ashrrev_i32_e32 v4, 6, v4
	v_lshrrev_b32_e32 v5, 26, v5
	v_lshlrev_b32_e32 v7, 3, v4
	v_add_u32_e32 v5, v6, v5
	v_and_b32_e32 v7, -16, v7
	v_ashrrev_i32_e32 v5, 6, v5
	v_add_u32_e32 v12, v5, v7
	v_mul_i32_i24_e32 v5, 64, v5
	v_lshlrev_b32_e32 v4, 5, v4
	v_sub_u32_e32 v5, v6, v5
	v_and_b32_e32 v4, 32, v4
	v_ashrrev_i16_sdwa v5, v146, sext(v5) dst_sel:DWORD dst_unused:UNUSED_PAD src0_sel:DWORD src1_sel:BYTE_0
	s_movk_i32 s8, 0x3000
	v_add_u32_e32 v45, 0, v0
	v_add_u32_sdwa v34, v4, sext(v5) dst_sel:DWORD dst_unused:UNUSED_PAD src0_sel:DWORD src1_sel:WORD_0
	v_mad_i64_i32 v[4:5], s[6:7], v12, s8, v[2:3]
	v_add_u32_e32 v6, 0x8000, v45
	v_add_u32_e32 v13, 0x2000, v0
	v_readfirstlane_b32 s6, v6
	v_ashrrev_i32_e32 v6, 31, v13
	v_lshrrev_b32_e32 v6, 22, v6
	v_add_u32_e32 v6, v13, v6
	v_ashrrev_i32_e32 v6, 10, v6
	v_mul_i32_i24_e32 v7, 0x400, v6
	v_sub_u32_e32 v7, v13, v7
	v_lshrrev_b32_e32 v8, 4, v7
	v_bitop3_b32 v7, v8, v7, 32 bitop3:0x6c
	v_ashrrev_i32_e32 v9, 31, v7
	v_lshrrev_b32_e32 v9, 26, v9
	v_lshlrev_b32_e32 v8, 3, v6
	v_add_u32_e32 v9, v7, v9
	v_and_b32_e32 v8, -16, v8
	v_ashrrev_i32_e32 v10, 6, v9
	v_add_u32_e32 v14, v10, v8
	v_and_b32_e32 v8, 0xc0, v9
	v_lshlrev_b32_e32 v6, 5, v6
	v_sub_u32_e32 v7, v7, v8
	v_and_b32_e32 v6, 32, v6
	v_ashrrev_i16_sdwa v7, v146, sext(v7) dst_sel:DWORD dst_unused:UNUSED_PAD src0_sel:DWORD src1_sel:BYTE_0
	s_mov_b32 m0, s6
	v_add_u32_sdwa v36, v6, sext(v7) dst_sel:DWORD dst_unused:UNUSED_PAD src0_sel:DWORD src1_sel:WORD_0
	v_mad_i64_i32 v[6:7], s[6:7], v14, s8, v[2:3]
	v_add_u32_e32 v8, 0xa000, v45
	v_add_u32_e32 v15, 0x4000, v0
	v_readfirstlane_b32 s6, v8
	v_ashrrev_i32_e32 v8, 31, v15
	v_lshrrev_b32_e32 v8, 22, v8
	v_add_u32_e32 v8, v15, v8
	v_ashrrev_i32_e32 v8, 10, v8
	v_mul_i32_i24_e32 v9, 0x400, v8
	v_sub_u32_e32 v9, v15, v9
	v_lshrrev_b32_e32 v10, 4, v9
	v_bitop3_b32 v9, v10, v9, 32 bitop3:0x6c
	v_ashrrev_i32_e32 v11, 31, v9
	v_lshrrev_b32_e32 v11, 26, v11
	v_add_u32_e32 v11, v9, v11
	v_ashrrev_i32_e32 v16, 6, v11
	v_and_b32_e32 v11, 0xc0, v11
	v_lshlrev_b32_e32 v10, 3, v8
	v_lshlrev_b32_e32 v8, 5, v8
	v_sub_u32_e32 v9, v9, v11
	v_ashrrev_i32_e32 v35, 31, v34
	v_and_b32_e32 v10, -16, v10
	v_and_b32_e32 v8, 32, v8
	v_ashrrev_i16_sdwa v9, v146, sext(v9) dst_sel:DWORD dst_unused:UNUSED_PAD src0_sel:DWORD src1_sel:BYTE_0
	v_lshl_add_u64 v[4:5], v[34:35], 1, v[4:5]
	v_add_u32_e32 v10, v16, v10
	v_add_u32_sdwa v8, v8, sext(v9) dst_sel:DWORD dst_unused:UNUSED_PAD src0_sel:DWORD src1_sel:WORD_0
	global_load_lds_dwordx4 v[4:5], off
	s_mov_b32 m0, s6
	v_mad_i64_i32 v[10:11], s[6:7], v10, s8, v[2:3]
	v_ashrrev_i32_e32 v9, 31, v8
	v_lshl_add_u64 v[8:9], v[8:9], 1, v[10:11]
	v_add_u32_e32 v10, 0xc000, v45
	v_add_u32_e32 v16, 0x6000, v0
	v_readfirstlane_b32 s6, v10
	v_ashrrev_i32_e32 v10, 31, v16
	v_lshrrev_b32_e32 v10, 22, v10
	v_add_u32_e32 v10, v16, v10
	v_ashrrev_i32_e32 v10, 10, v10
	v_mul_i32_i24_e32 v11, 0x400, v10
	v_sub_u32_e32 v11, v16, v11
	v_lshrrev_b32_e32 v17, 4, v11
	v_bitop3_b32 v11, v17, v11, 32 bitop3:0x6c
	v_ashrrev_i32_e32 v18, 31, v11
	v_lshrrev_b32_e32 v18, 26, v18
	v_add_u32_e32 v18, v11, v18
	v_ashrrev_i32_e32 v19, 6, v18
	v_and_b32_e32 v18, 0xc0, v18
	v_lshlrev_b32_e32 v17, 3, v10
	v_lshlrev_b32_e32 v10, 5, v10
	v_sub_u32_e32 v11, v11, v18
	v_ashrrev_i32_e32 v37, 31, v36
	v_and_b32_e32 v17, -16, v17
	v_and_b32_e32 v10, 32, v10
	v_ashrrev_i16_sdwa v11, v146, sext(v11) dst_sel:DWORD dst_unused:UNUSED_PAD src0_sel:DWORD src1_sel:BYTE_0
	v_lshl_add_u64 v[6:7], v[36:37], 1, v[6:7]
	v_add_u32_e32 v17, v19, v17
	v_add_u32_sdwa v10, v10, sext(v11) dst_sel:DWORD dst_unused:UNUSED_PAD src0_sel:DWORD src1_sel:WORD_0
	global_load_lds_dwordx4 v[6:7], off
	s_mov_b32 m0, s6
	v_mad_i64_i32 v[2:3], s[6:7], v17, s8, v[2:3]
	v_ashrrev_i32_e32 v11, 31, v10
	v_lshl_add_u64 v[2:3], v[10:11], 1, v[2:3]
	v_add_u32_e32 v10, 0xe000, v45
	global_load_lds_dwordx4 v[8:9], off
	v_readfirstlane_b32 s6, v10
	s_mov_b32 m0, s6
	s_add_i32 s6, 0, 0x10000
	v_add_u32_e32 v0, s6, v0
	global_load_lds_dwordx4 v[2:3], off
	v_readfirstlane_b32 s7, v0
	v_add_u32_e32 v0, s6, v13
	v_lshl_add_u64 v[4:5], v[4:5], 0, s[30:31]
	s_mov_b32 m0, s7
	v_readfirstlane_b32 s7, v0
	v_add_u32_e32 v0, s6, v15
	global_load_lds_dwordx4 v[4:5], off
	v_lshl_add_u64 v[4:5], v[6:7], 0, s[30:31]
	s_mov_b32 m0, s7
	v_readfirstlane_b32 s7, v0
	v_add_u32_e32 v0, s6, v16
	global_load_lds_dwordx4 v[4:5], off
	v_lshl_add_u64 v[4:5], v[8:9], 0, s[30:31]
	s_mov_b32 m0, s7
	v_readfirstlane_b32 s7, v0
	v_or_b32_e32 v54, s20, v44
	global_load_lds_dwordx4 v[4:5], off
	v_lshl_add_u64 v[2:3], v[2:3], 0, s[30:31]
	s_mov_b32 m0, s7
	v_ashrrev_i32_e32 v55, 31, v54
	v_readlane_b32 s68, v214, 40
	global_load_lds_dwordx4 v[2:3], off
	v_lshlrev_b64 v[2:3], 16, v[54:55]
	v_readlane_b32 s78, v214, 50
	v_readlane_b32 s79, v214, 51
	v_lshl_add_u64 v[10:11], s[78:79], 0, v[2:3]
	v_lshlrev_b32_e32 v2, 7, v12
	v_ashrrev_i32_e32 v3, 31, v2
	v_lshl_add_u64 v[2:3], v[2:3], 2, v[10:11]
	v_lshl_add_u64 v[22:23], v[34:35], 2, v[2:3]
	global_load_dwordx4 v[2:5], v[22:23], off
	global_load_dwordx4 v[6:9], v[22:23], off offset:16
	v_lshlrev_b32_e32 v12, 7, v14
	v_ashrrev_i32_e32 v13, 31, v12
	v_lshl_add_u64 v[10:11], v[12:13], 2, v[10:11]
	v_lshl_add_u64 v[30:31], v[36:37], 2, v[10:11]
	global_load_dwordx4 v[10:13], v[30:31], off
	global_load_dwordx4 v[14:17], v[30:31], off offset:16
	global_load_dwordx4 v[18:21], v[22:23], off offset:256
	s_nop 0
	global_load_dwordx4 v[22:25], v[22:23], off offset:272
	s_nop 0
	global_load_dwordx4 v[26:29], v[30:31], off offset:256
	s_nop 0
	global_load_dwordx4 v[30:33], v[30:31], off offset:272
	s_waitcnt vmcnt(0) lgkmcnt(0)
	s_barrier
	v_lshlrev_b32_e32 v0, 2, v34
	s_add_i32 s7, 0, 0x24000
	v_add_u32_e32 v37, s7, v0
	ds_read2_b32 v[34:35], v37 offset1:1
	ds_read2_b32 v[38:39], v37 offset0:2 offset1:3
	ds_read2_b32 v[40:41], v37 offset0:4 offset1:5
	ds_read2_b32 v[42:43], v37 offset0:6 offset1:7
	v_bfe_u32 v58, v56, 4, 2
	v_lshlrev_b32_e32 v57, 8, v44
	v_readlane_b32 s69, v214, 41
	v_readlane_b32 s70, v214, 42
	v_readlane_b32 s71, v214, 43
	v_readlane_b32 s72, v214, 44
	v_readlane_b32 s73, v214, 45
	v_readlane_b32 s74, v214, 46
	v_readlane_b32 s75, v214, 47
	v_readlane_b32 s76, v214, 48
	v_readlane_b32 s77, v214, 49
	v_readlane_b32 s80, v214, 52
	v_readlane_b32 s81, v214, 53
	v_readlane_b32 s82, v214, 54
	v_readlane_b32 s83, v214, 55
	s_waitcnt vmcnt(7) lgkmcnt(3)
	v_pk_mul_f32 v[2:3], v[2:3], v[34:35]
	s_waitcnt lgkmcnt(2)
	v_pk_mul_f32 v[4:5], v[4:5], v[38:39]
	v_cvt_pk_bf16_f32 v2, v2, v3
	v_cvt_pk_bf16_f32 v3, v4, v5
	s_waitcnt vmcnt(6) lgkmcnt(1)
	v_pk_mul_f32 v[4:5], v[6:7], v[40:41]
	s_waitcnt lgkmcnt(0)
	v_pk_mul_f32 v[6:7], v[8:9], v[42:43]
	v_cvt_pk_bf16_f32 v4, v4, v5
	v_cvt_pk_bf16_f32 v5, v6, v7
	v_lshlrev_b32_e32 v34, 2, v36
	ds_write_b128 v45, v[2:5]
	v_add_u32_e32 v8, s7, v34
	ds_read2_b32 v[2:3], v8 offset1:1
	ds_read2_b32 v[4:5], v8 offset0:2 offset1:3
	ds_read2_b32 v[6:7], v8 offset0:4 offset1:5
	ds_read2_b32 v[8:9], v8 offset0:6 offset1:7
	v_readlane_b32 s7, v214, 35
	s_waitcnt vmcnt(5) lgkmcnt(2)
	v_pk_mul_f32 v[4:5], v[12:13], v[4:5]
	v_pk_mul_f32 v[2:3], v[10:11], v[2:3]
	v_add_u32_e32 v0, s7, v0
	v_cvt_pk_bf16_f32 v2, v2, v3
	v_cvt_pk_bf16_f32 v3, v4, v5
	s_waitcnt vmcnt(4) lgkmcnt(1)
	v_pk_mul_f32 v[4:5], v[14:15], v[6:7]
	s_waitcnt lgkmcnt(0)
	v_pk_mul_f32 v[6:7], v[16:17], v[8:9]
	v_cvt_pk_bf16_f32 v4, v4, v5
	v_cvt_pk_bf16_f32 v5, v6, v7
	ds_write_b128 v45, v[2:5] offset:8192
	ds_read2_b32 v[2:3], v0 offset1:1
	ds_read2_b32 v[4:5], v0 offset0:2 offset1:3
	ds_read2_b32 v[6:7], v0 offset0:4 offset1:5
	ds_read2_b32 v[8:9], v0 offset0:6 offset1:7
	v_add_u32_e32 v0, s7, v34
	v_and_b32_e32 v10, 15, v56
	s_waitcnt vmcnt(3) lgkmcnt(2)
	v_pk_mul_f32 v[4:5], v[20:21], v[4:5]
	v_pk_mul_f32 v[2:3], v[18:19], v[2:3]
	s_movk_i32 s7, 0x6000
	v_cvt_pk_bf16_f32 v2, v2, v3
	v_cvt_pk_bf16_f32 v3, v4, v5
	s_waitcnt vmcnt(2) lgkmcnt(1)
	v_pk_mul_f32 v[4:5], v[22:23], v[6:7]
	s_waitcnt lgkmcnt(0)
	v_pk_mul_f32 v[6:7], v[24:25], v[8:9]
	v_cvt_pk_bf16_f32 v4, v4, v5
	v_cvt_pk_bf16_f32 v5, v6, v7
	ds_write_b128 v45, v[2:5] offset:16384
	ds_read2_b32 v[2:3], v0 offset1:1
	ds_read2_b32 v[4:5], v0 offset0:2 offset1:3
	ds_read2_b32 v[6:7], v0 offset0:4 offset1:5
	ds_read2_b32 v[8:9], v0 offset0:6 offset1:7
	v_ashrrev_i32_e32 v0, 2, v56
	v_and_b32_e32 v0, 0xffffffc0, v0
	s_waitcnt vmcnt(1) lgkmcnt(2)
	v_pk_mul_f32 v[4:5], v[28:29], v[4:5]
	v_pk_mul_f32 v[2:3], v[26:27], v[2:3]
	v_or_b32_e32 v114, v0, v10
	v_cvt_pk_bf16_f32 v2, v2, v3
	v_cvt_pk_bf16_f32 v3, v4, v5
	s_waitcnt vmcnt(0) lgkmcnt(1)
	v_pk_mul_f32 v[4:5], v[30:31], v[6:7]
	s_waitcnt lgkmcnt(0)
	v_pk_mul_f32 v[6:7], v[32:33], v[8:9]
	v_cvt_pk_bf16_f32 v4, v4, v5
	v_cvt_pk_bf16_f32 v5, v6, v7
	ds_write_b128 v45, v[2:5] offset:24576
	v_lshlrev_b32_e32 v2, 4, v58
	v_lshlrev_b32_e32 v4, 2, v56
	v_lshl_or_b32 v3, v10, 6, v2
	v_lshlrev_b32_e32 v0, 7, v0
	v_and_b32_e32 v4, 32, v4
	v_bitop3_b32 v0, v3, v0, v4 bitop3:0xde
	v_lshlrev_b32_e32 v3, 6, v56
	v_and_b32_e32 v3, 0x3c0, v3
	v_lshlrev_b32_e32 v5, 7, v56
	v_bitop3_b32 v2, v3, v4, v2 bitop3:0x36
	s_waitcnt vmcnt(0)
	s_waitcnt lgkmcnt(0)
	s_barrier
	v_add_u32_e32 v46, 0, v0
	v_and_or_b32 v59, v5, s7, v2
	ds_read_b128 v[2:5], v46 offset:0
	ds_read_b128 v[6:9], v46 offset:2048
	ds_read_b128 v[10:13], v46 offset:4096
	s_add_i32 s7, 0, 0x8000
	ds_read_b128 v[14:17], v46 offset:6144
	v_add_u32_e32 v61, s7, v59
	ds_read_b128 v[18:21], v61 offset:0
	ds_read_b128 v[22:25], v61 offset:2048
	ds_read_b128 v[26:29], v61 offset:4096
	ds_read_b128 v[30:33], v61 offset:6144
	ds_read_b128 v[34:37], v46 offset:1024
	ds_read_b128 v[38:41], v46 offset:3072
	ds_read_b128 v[42:45], v46 offset:5120
	ds_read_b128 v[46:49], v46 offset:7168
	ds_read_b128 v[50:53], v61 offset:1024
	ds_read_b128 v[62:65], v61 offset:3072
	ds_read_b128 v[66:69], v61 offset:5120
	ds_read_b128 v[70:73], v61 offset:7168
	s_waitcnt lgkmcnt(8)
	s_nop 0
	v_mfma_f32_16x16x32_bf16 v[74:77], v[18:21], v[2:5], 0
	v_mfma_f32_16x16x32_bf16 v[78:81], v[22:25], v[2:5], 0
	v_mfma_f32_16x16x32_bf16 v[82:85], v[26:29], v[2:5], 0
	v_mfma_f32_16x16x32_bf16 v[2:5], v[30:33], v[2:5], 0
	v_mfma_f32_16x16x32_bf16 v[86:89], v[18:21], v[6:9], 0
	v_mfma_f32_16x16x32_bf16 v[90:93], v[22:25], v[6:9], 0
	v_mfma_f32_16x16x32_bf16 v[94:97], v[26:29], v[6:9], 0
	v_mfma_f32_16x16x32_bf16 v[6:9], v[30:33], v[6:9], 0
	v_mfma_f32_16x16x32_bf16 v[98:101], v[18:21], v[10:13], 0
	v_mfma_f32_16x16x32_bf16 v[102:105], v[22:25], v[10:13], 0
	v_mfma_f32_16x16x32_bf16 v[106:109], v[26:29], v[10:13], 0
	v_mfma_f32_16x16x32_bf16 v[10:13], v[30:33], v[10:13], 0
	v_mfma_f32_16x16x32_bf16 v[18:21], v[18:21], v[14:17], 0
	v_mfma_f32_16x16x32_bf16 v[22:25], v[22:25], v[14:17], 0
	v_mfma_f32_16x16x32_bf16 v[26:29], v[26:29], v[14:17], 0
	v_mfma_f32_16x16x32_bf16 v[14:17], v[30:33], v[14:17], 0
	s_waitcnt lgkmcnt(0)
	v_mfma_f32_16x16x32_bf16 v[2:5], v[70:73], v[34:37], v[2:5]
	v_mfma_f32_16x16x32_bf16 v[30:33], v[50:53], v[34:37], v[74:77]
	v_mfma_f32_16x16x32_bf16 v[74:77], v[62:65], v[34:37], v[78:81]
	v_mfma_f32_16x16x32_bf16 v[78:81], v[66:69], v[34:37], v[82:85]
	v_mfma_f32_16x16x32_bf16 v[34:37], v[50:53], v[38:41], v[86:89]
	v_mfma_f32_16x16x32_bf16 v[82:85], v[62:65], v[38:41], v[90:93]
	v_mfma_f32_16x16x32_bf16 v[86:89], v[66:69], v[38:41], v[94:97]
	v_mfma_f32_16x16x32_bf16 v[6:9], v[70:73], v[38:41], v[6:9]
	v_mfma_f32_16x16x32_bf16 v[38:41], v[50:53], v[42:45], v[98:101]
	v_mfma_f32_16x16x32_bf16 v[90:93], v[62:65], v[42:45], v[102:105]
	v_mfma_f32_16x16x32_bf16 v[94:97], v[66:69], v[42:45], v[106:109]
	v_mfma_f32_16x16x32_bf16 v[10:13], v[70:73], v[42:45], v[10:13]
	v_mfma_f32_16x16x32_bf16 v[18:21], v[50:53], v[46:49], v[18:21]
	v_mfma_f32_16x16x32_bf16 v[22:25], v[62:65], v[46:49], v[22:25]
	v_mfma_f32_16x16x32_bf16 v[26:29], v[66:69], v[46:49], v[26:29]
	v_mfma_f32_16x16x32_bf16 v[14:17], v[70:73], v[46:49], v[14:17]
	s_add_i32 s7, 0, 0x4000
	v_add_u32_e32 v0, s7, v0
	ds_read_b128 v[42:45], v0 offset:0
	ds_read_b128 v[46:49], v0 offset:2048
	ds_read_b128 v[50:53], v0 offset:4096
	ds_read_b128 v[62:65], v0 offset:6144
	v_add_u32_e32 v59, s6, v59
	ds_read_b128 v[66:69], v59 offset:0
	ds_read_b128 v[70:73], v59 offset:2048
	ds_read_b128 v[98:101], v59 offset:4096
	ds_read_b128 v[102:105], v59 offset:6144
	ds_read_b128 v[106:109], v0 offset:1024
	ds_read_b128 v[110:113], v0 offset:3072
	ds_read_b128 v[120:123], v0 offset:5120
	ds_read_b128 v[124:127], v0 offset:7168
	ds_read_b128 v[134:137], v59 offset:1024
	ds_read_b128 v[138:141], v59 offset:3072
	ds_read_b128 v[162:165], v59 offset:5120
	ds_read_b128 v[166:169], v59 offset:7168
	s_waitcnt lgkmcnt(8)
	s_nop 0
	v_mfma_f32_16x16x32_bf16 v[2:5], v[102:105], v[42:45], v[2:5]
	v_mfma_f32_16x16x32_bf16 v[30:33], v[66:69], v[42:45], v[30:33]
	v_mfma_f32_16x16x32_bf16 v[74:77], v[70:73], v[42:45], v[74:77]
	v_mfma_f32_16x16x32_bf16 v[78:81], v[98:101], v[42:45], v[78:81]
	v_mfma_f32_16x16x32_bf16 v[34:37], v[66:69], v[46:49], v[34:37]
	v_mfma_f32_16x16x32_bf16 v[42:45], v[70:73], v[46:49], v[82:85]
	v_mfma_f32_16x16x32_bf16 v[82:85], v[98:101], v[46:49], v[86:89]
	v_mfma_f32_16x16x32_bf16 v[6:9], v[102:105], v[46:49], v[6:9]
	v_mfma_f32_16x16x32_bf16 v[86:89], v[66:69], v[50:53], v[38:41]
	v_mfma_f32_16x16x32_bf16 v[90:93], v[70:73], v[50:53], v[90:93]
	v_mfma_f32_16x16x32_bf16 v[94:97], v[98:101], v[50:53], v[94:97]
	v_mfma_f32_16x16x32_bf16 v[10:13], v[102:105], v[50:53], v[10:13]
	v_mfma_f32_16x16x32_bf16 v[66:69], v[66:69], v[62:65], v[18:21]
	v_mfma_f32_16x16x32_bf16 v[70:73], v[70:73], v[62:65], v[22:25]
	v_mfma_f32_16x16x32_bf16 v[98:101], v[98:101], v[62:65], v[26:29]
	v_mfma_f32_16x16x32_bf16 v[62:65], v[102:105], v[62:65], v[14:17]
	s_waitcnt lgkmcnt(0)
	v_mfma_f32_16x16x32_bf16 v[50:53], v[166:169], v[106:109], v[2:5]
	v_mfma_f32_16x16x32_bf16 v[2:5], v[166:169], v[124:127], v[62:65]
	v_mfma_f32_16x16x32_bf16 v[102:105], v[134:137], v[106:109], v[30:33]
	v_mfma_f32_16x16x32_bf16 v[74:77], v[138:141], v[106:109], v[74:77]
	v_mfma_f32_16x16x32_bf16 v[78:81], v[162:165], v[106:109], v[78:81]
	v_mfma_f32_16x16x32_bf16 v[46:49], v[134:137], v[110:113], v[34:37]
	v_mfma_f32_16x16x32_bf16 v[42:45], v[138:141], v[110:113], v[42:45]
	v_mfma_f32_16x16x32_bf16 v[38:41], v[162:165], v[110:113], v[82:85]
	v_mfma_f32_16x16x32_bf16 v[34:37], v[166:169], v[110:113], v[6:9]
	v_mfma_f32_16x16x32_bf16 v[30:33], v[134:137], v[120:123], v[86:89]
	v_mfma_f32_16x16x32_bf16 v[26:29], v[138:141], v[120:123], v[90:93]
	v_mfma_f32_16x16x32_bf16 v[22:25], v[162:165], v[120:123], v[94:97]
	v_mfma_f32_16x16x32_bf16 v[18:21], v[166:169], v[120:123], v[10:13]
	v_mfma_f32_16x16x32_bf16 v[14:17], v[134:137], v[124:127], v[66:69]
	v_mfma_f32_16x16x32_bf16 v[10:13], v[138:141], v[124:127], v[70:73]
	v_mfma_f32_16x16x32_bf16 v[6:9], v[162:165], v[124:127], v[98:101]
	v_lshlrev_b64 v[54:55], 9, v[54:55]
	v_lshl_add_u64 v[54:55], s[80:81], 0, v[54:55]
	v_ashrrev_i32_e32 v115, 31, v114
	v_and_or_b32 v0, v56, s57, v57
	v_lshl_add_u64 v[56:57], v[114:115], 2, v[54:55]
	v_add_u32_e32 v54, v114, v60
	v_ashrrev_i32_e32 v55, 31, v54
	v_readlane_b32 s8, v217, 39
	v_lshl_or_b32 v0, v58, 2, v0
	v_lshlrev_b64 v[60:61], 11, v[54:55]
	v_readlane_b32 s9, v217, 40
	v_lshlrev_b32_e32 v59, 2, v0
	v_readlane_b32 s6, v217, 24
	v_lshl_add_u64 v[64:65], s[8:9], 0, v[60:61]
	v_lshlrev_b32_e32 v0, 1, v0
	v_readlane_b32 s7, v217, 25
	v_lshl_add_u64 v[64:65], v[64:65], 0, v[0:1]
	v_lshl_add_u64 v[66:67], s[6:7], 0, v[60:61]
	v_lshl_add_u64 v[66:67], v[66:67], 0, v[0:1]
	s_mov_b64 vcc, 0x8000
	global_load_dword v250, v[56:57], off
	global_load_dword v252, v[56:57], off offset:64
	global_load_dword v254, v[56:57], off offset:128
	global_load_dword v70, v[56:57], off offset:192
	global_load_dwordx4 v[106:109], v59, s[86:87]
	global_load_dwordx4 v[110:113], v59, s[86:87] offset:64
	global_load_dwordx4 v[120:123], v59, s[86:87] offset:128
	global_load_dwordx4 v[124:127], v59, s[86:87] offset:192
	global_load_dwordx2 v[218:219], v[64:65], off
	global_load_dwordx2 v[220:221], v[64:65], off offset:32
	global_load_dwordx2 v[222:223], v[64:65], off offset:64
	global_load_dwordx2 v[224:225], v[64:65], off offset:96
	v_lshl_add_u64 v[64:65], v[64:65], 0, vcc
	global_load_dwordx2 v[226:227], v[64:65], off
	global_load_dwordx2 v[228:229], v[64:65], off offset:32
	global_load_dwordx2 v[230:231], v[64:65], off offset:64
	global_load_dwordx2 v[232:233], v[64:65], off offset:96
	v_lshl_add_u64 v[64:65], v[64:65], 0, vcc
	global_load_dwordx2 v[234:235], v[64:65], off
	global_load_dwordx2 v[236:237], v[64:65], off offset:32
	global_load_dwordx2 v[238:239], v[64:65], off offset:64
	global_load_dwordx2 v[240:241], v[64:65], off offset:96
	v_lshl_add_u64 v[64:65], v[64:65], 0, vcc
	global_load_dwordx2 v[242:243], v[64:65], off
	global_load_dwordx2 v[244:245], v[64:65], off offset:32
	global_load_dwordx2 v[246:247], v[64:65], off offset:64
	global_load_dwordx2 v[248:249], v[64:65], off offset:96
	s_waitcnt vmcnt(12)
	v_pk_fma_f32 v[102:103], v[102:103], v[106:107], v[250:251] op_sel_hi:[1,1,0]
	v_pk_fma_f32 v[104:105], v[104:105], v[108:109], v[250:251] op_sel_hi:[1,1,0]
	v_lshlrev_b32_e32 v86, 16, v218
	v_and_b32_e32 v87, 0xffff0000, v218
	v_lshlrev_b32_e32 v88, 16, v219
	v_and_b32_e32 v89, 0xffff0000, v219
	v_pk_mul_f32 v[102:103], v[102:103], v[86:87]
	v_pk_mul_f32 v[104:105], v[104:105], v[88:89]
	s_nop 0
	v_cvt_pk_bf16_f32 v102, v102, v103
	v_cvt_pk_bf16_f32 v103, v104, v105
	global_store_dwordx2 v[66:67], v[102:103], off
	v_pk_fma_f32 v[74:75], v[74:75], v[110:111], v[250:251] op_sel_hi:[1,1,0]
	v_pk_fma_f32 v[76:77], v[76:77], v[112:113], v[250:251] op_sel_hi:[1,1,0]
	v_lshlrev_b32_e32 v90, 16, v220
	v_and_b32_e32 v91, 0xffff0000, v220
	v_lshlrev_b32_e32 v92, 16, v221
	v_and_b32_e32 v93, 0xffff0000, v221
	v_pk_mul_f32 v[74:75], v[74:75], v[90:91]
	v_pk_mul_f32 v[76:77], v[76:77], v[92:93]
	s_nop 0
	v_cvt_pk_bf16_f32 v74, v74, v75
	v_cvt_pk_bf16_f32 v75, v76, v77
	global_store_dwordx2 v[66:67], v[74:75], off offset:32
	v_pk_fma_f32 v[78:79], v[78:79], v[120:121], v[250:251] op_sel_hi:[1,1,0]
	v_pk_fma_f32 v[80:81], v[80:81], v[122:123], v[250:251] op_sel_hi:[1,1,0]
	v_lshlrev_b32_e32 v86, 16, v222
	v_and_b32_e32 v87, 0xffff0000, v222
	v_lshlrev_b32_e32 v88, 16, v223
	v_and_b32_e32 v89, 0xffff0000, v223
	v_pk_mul_f32 v[78:79], v[78:79], v[86:87]
	v_pk_mul_f32 v[80:81], v[80:81], v[88:89]
	s_nop 0
	v_cvt_pk_bf16_f32 v78, v78, v79
	v_cvt_pk_bf16_f32 v79, v80, v81
	global_store_dwordx2 v[66:67], v[78:79], off offset:64
	v_pk_fma_f32 v[50:51], v[50:51], v[124:125], v[250:251] op_sel_hi:[1,1,0]
	v_pk_fma_f32 v[52:53], v[52:53], v[126:127], v[250:251] op_sel_hi:[1,1,0]
	v_lshlrev_b32_e32 v90, 16, v224
	v_and_b32_e32 v91, 0xffff0000, v224
	v_lshlrev_b32_e32 v92, 16, v225
	v_and_b32_e32 v93, 0xffff0000, v225
	v_pk_mul_f32 v[50:51], v[50:51], v[90:91]
	v_pk_mul_f32 v[52:53], v[52:53], v[92:93]
	s_nop 0
	v_cvt_pk_bf16_f32 v50, v50, v51
	v_cvt_pk_bf16_f32 v51, v52, v53
	global_store_dwordx2 v[66:67], v[50:51], off offset:96
	v_lshl_add_u64 v[66:67], v[66:67], 0, vcc
	s_waitcnt vmcnt(12)
	v_pk_fma_f32 v[46:47], v[46:47], v[106:107], v[252:253] op_sel_hi:[1,1,0]
	v_pk_fma_f32 v[48:49], v[48:49], v[108:109], v[252:253] op_sel_hi:[1,1,0]
	v_lshlrev_b32_e32 v86, 16, v226
	v_and_b32_e32 v87, 0xffff0000, v226
	v_lshlrev_b32_e32 v88, 16, v227
	v_and_b32_e32 v89, 0xffff0000, v227
	v_pk_mul_f32 v[46:47], v[46:47], v[86:87]
	v_pk_mul_f32 v[48:49], v[48:49], v[88:89]
	s_nop 0
	v_cvt_pk_bf16_f32 v46, v46, v47
	v_cvt_pk_bf16_f32 v47, v48, v49
	global_store_dwordx2 v[66:67], v[46:47], off
	v_pk_fma_f32 v[42:43], v[42:43], v[110:111], v[252:253] op_sel_hi:[1,1,0]
	v_pk_fma_f32 v[44:45], v[44:45], v[112:113], v[252:253] op_sel_hi:[1,1,0]
	v_lshlrev_b32_e32 v90, 16, v228
	v_and_b32_e32 v91, 0xffff0000, v228
	v_lshlrev_b32_e32 v92, 16, v229
	v_and_b32_e32 v93, 0xffff0000, v229
	v_pk_mul_f32 v[42:43], v[42:43], v[90:91]
	v_pk_mul_f32 v[44:45], v[44:45], v[92:93]
	s_nop 0
	v_cvt_pk_bf16_f32 v42, v42, v43
	v_cvt_pk_bf16_f32 v43, v44, v45
	global_store_dwordx2 v[66:67], v[42:43], off offset:32
	v_pk_fma_f32 v[38:39], v[38:39], v[120:121], v[252:253] op_sel_hi:[1,1,0]
	v_pk_fma_f32 v[40:41], v[40:41], v[122:123], v[252:253] op_sel_hi:[1,1,0]
	v_lshlrev_b32_e32 v86, 16, v230
	v_and_b32_e32 v87, 0xffff0000, v230
	v_lshlrev_b32_e32 v88, 16, v231
	v_and_b32_e32 v89, 0xffff0000, v231
	v_pk_mul_f32 v[38:39], v[38:39], v[86:87]
	v_pk_mul_f32 v[40:41], v[40:41], v[88:89]
	s_nop 0
	v_cvt_pk_bf16_f32 v38, v38, v39
	v_cvt_pk_bf16_f32 v39, v40, v41
	global_store_dwordx2 v[66:67], v[38:39], off offset:64
	v_pk_fma_f32 v[34:35], v[34:35], v[124:125], v[252:253] op_sel_hi:[1,1,0]
	v_pk_fma_f32 v[36:37], v[36:37], v[126:127], v[252:253] op_sel_hi:[1,1,0]
	v_lshlrev_b32_e32 v90, 16, v232
	v_and_b32_e32 v91, 0xffff0000, v232
	v_lshlrev_b32_e32 v92, 16, v233
	v_and_b32_e32 v93, 0xffff0000, v233
	v_pk_mul_f32 v[34:35], v[34:35], v[90:91]
	v_pk_mul_f32 v[36:37], v[36:37], v[92:93]
	s_nop 0
	v_cvt_pk_bf16_f32 v34, v34, v35
	v_cvt_pk_bf16_f32 v35, v36, v37
	global_store_dwordx2 v[66:67], v[34:35], off offset:96
	v_lshl_add_u64 v[66:67], v[66:67], 0, vcc
	s_waitcnt vmcnt(12)
	v_pk_fma_f32 v[30:31], v[30:31], v[106:107], v[254:255] op_sel_hi:[1,1,0]
	v_pk_fma_f32 v[32:33], v[32:33], v[108:109], v[254:255] op_sel_hi:[1,1,0]
	v_lshlrev_b32_e32 v86, 16, v234
	v_and_b32_e32 v87, 0xffff0000, v234
	v_lshlrev_b32_e32 v88, 16, v235
	v_and_b32_e32 v89, 0xffff0000, v235
	v_pk_mul_f32 v[30:31], v[30:31], v[86:87]
	v_pk_mul_f32 v[32:33], v[32:33], v[88:89]
	s_nop 0
	v_cvt_pk_bf16_f32 v30, v30, v31
	v_cvt_pk_bf16_f32 v31, v32, v33
	global_store_dwordx2 v[66:67], v[30:31], off
	v_pk_fma_f32 v[26:27], v[26:27], v[110:111], v[254:255] op_sel_hi:[1,1,0]
	v_pk_fma_f32 v[28:29], v[28:29], v[112:113], v[254:255] op_sel_hi:[1,1,0]
	v_lshlrev_b32_e32 v90, 16, v236
	v_and_b32_e32 v91, 0xffff0000, v236
	v_lshlrev_b32_e32 v92, 16, v237
	v_and_b32_e32 v93, 0xffff0000, v237
	v_pk_mul_f32 v[26:27], v[26:27], v[90:91]
	v_pk_mul_f32 v[28:29], v[28:29], v[92:93]
	s_nop 0
	v_cvt_pk_bf16_f32 v26, v26, v27
	v_cvt_pk_bf16_f32 v27, v28, v29
	global_store_dwordx2 v[66:67], v[26:27], off offset:32
	v_pk_fma_f32 v[22:23], v[22:23], v[120:121], v[254:255] op_sel_hi:[1,1,0]
	v_pk_fma_f32 v[24:25], v[24:25], v[122:123], v[254:255] op_sel_hi:[1,1,0]
	v_lshlrev_b32_e32 v86, 16, v238
	v_and_b32_e32 v87, 0xffff0000, v238
	v_lshlrev_b32_e32 v88, 16, v239
	v_and_b32_e32 v89, 0xffff0000, v239
	v_pk_mul_f32 v[22:23], v[22:23], v[86:87]
	v_pk_mul_f32 v[24:25], v[24:25], v[88:89]
	s_nop 0
	v_cvt_pk_bf16_f32 v22, v22, v23
	v_cvt_pk_bf16_f32 v23, v24, v25
	global_store_dwordx2 v[66:67], v[22:23], off offset:64
	v_pk_fma_f32 v[18:19], v[18:19], v[124:125], v[254:255] op_sel_hi:[1,1,0]
	v_pk_fma_f32 v[20:21], v[20:21], v[126:127], v[254:255] op_sel_hi:[1,1,0]
	v_lshlrev_b32_e32 v90, 16, v240
	v_and_b32_e32 v91, 0xffff0000, v240
	v_lshlrev_b32_e32 v92, 16, v241
	v_and_b32_e32 v93, 0xffff0000, v241
	v_pk_mul_f32 v[18:19], v[18:19], v[90:91]
	v_pk_mul_f32 v[20:21], v[20:21], v[92:93]
	s_nop 0
	v_cvt_pk_bf16_f32 v18, v18, v19
	v_cvt_pk_bf16_f32 v19, v20, v21
	global_store_dwordx2 v[66:67], v[18:19], off offset:96
	v_lshl_add_u64 v[66:67], v[66:67], 0, vcc
	s_waitcnt vmcnt(12)
	v_pk_fma_f32 v[14:15], v[14:15], v[106:107], v[70:71] op_sel_hi:[1,1,0]
	v_pk_fma_f32 v[16:17], v[16:17], v[108:109], v[70:71] op_sel_hi:[1,1,0]
	v_lshlrev_b32_e32 v86, 16, v242
	v_and_b32_e32 v87, 0xffff0000, v242
	v_lshlrev_b32_e32 v88, 16, v243
	v_and_b32_e32 v89, 0xffff0000, v243
	v_pk_mul_f32 v[14:15], v[14:15], v[86:87]
	v_pk_mul_f32 v[16:17], v[16:17], v[88:89]
	s_nop 0
	v_cvt_pk_bf16_f32 v14, v14, v15
	v_cvt_pk_bf16_f32 v15, v16, v17
	global_store_dwordx2 v[66:67], v[14:15], off
	v_pk_fma_f32 v[10:11], v[10:11], v[110:111], v[70:71] op_sel_hi:[1,1,0]
	v_pk_fma_f32 v[12:13], v[12:13], v[112:113], v[70:71] op_sel_hi:[1,1,0]
	v_lshlrev_b32_e32 v90, 16, v244
	v_and_b32_e32 v91, 0xffff0000, v244
	v_lshlrev_b32_e32 v92, 16, v245
	v_and_b32_e32 v93, 0xffff0000, v245
	v_pk_mul_f32 v[10:11], v[10:11], v[90:91]
	v_pk_mul_f32 v[12:13], v[12:13], v[92:93]
	s_nop 0
	v_cvt_pk_bf16_f32 v10, v10, v11
	v_cvt_pk_bf16_f32 v11, v12, v13
	global_store_dwordx2 v[66:67], v[10:11], off offset:32
	v_pk_fma_f32 v[6:7], v[6:7], v[120:121], v[70:71] op_sel_hi:[1,1,0]
	v_pk_fma_f32 v[8:9], v[8:9], v[122:123], v[70:71] op_sel_hi:[1,1,0]
	v_lshlrev_b32_e32 v86, 16, v246
	v_and_b32_e32 v87, 0xffff0000, v246
	v_lshlrev_b32_e32 v88, 16, v247
	v_and_b32_e32 v89, 0xffff0000, v247
	v_pk_mul_f32 v[6:7], v[6:7], v[86:87]
	v_pk_mul_f32 v[8:9], v[8:9], v[88:89]
	s_nop 0
	v_cvt_pk_bf16_f32 v6, v6, v7
	v_cvt_pk_bf16_f32 v7, v8, v9
	global_store_dwordx2 v[66:67], v[6:7], off offset:64
	v_pk_fma_f32 v[2:3], v[2:3], v[124:125], v[70:71] op_sel_hi:[1,1,0]
	v_pk_fma_f32 v[4:5], v[4:5], v[126:127], v[70:71] op_sel_hi:[1,1,0]
	v_lshlrev_b32_e32 v90, 16, v248
	v_and_b32_e32 v91, 0xffff0000, v248
	v_lshlrev_b32_e32 v92, 16, v249
	v_and_b32_e32 v93, 0xffff0000, v249
	v_pk_mul_f32 v[2:3], v[2:3], v[90:91]
	v_pk_mul_f32 v[4:5], v[4:5], v[92:93]
	s_nop 0
	v_cvt_pk_bf16_f32 v2, v2, v3
	v_cvt_pk_bf16_f32 v3, v4, v5
	global_store_dwordx2 v[66:67], v[2:3], off offset:96
